# grid barrier moved in front of the two small memory-projection GEMMs so they overlap with the prep phase (prep on workgroups 0-127 only)
# baseline (speedup 1.0000x reference)
; __device__ __forceinline__ unsigned xb_ld(unsigned* p)              { return __hip_atomic_load(p, __ATOMIC_RELAXED, __HIP_MEMORY_SCOPE_AGENT); }
; __device__ __forceinline__ unsigned xb_add(unsigned* p, unsigned v) { return __hip_atomic_fetch_add(p, v, __ATOMIC_RELAXED, __HIP_MEMORY_SCOPE_AGENT); }
; __device__ __forceinline__ void xcd_barrier_complete(unsigned* bar, unsigned x, unsigned& nloc, unsigned& nx) {
;     const unsigned G = gridDim.x * gridDim.y * gridDim.z;
;     unsigned sum, cnt, mine, sp = 0u;
;     for (;;) {
;         sum = 0u; cnt = 0u; mine = 0u;
; #pragma unroll
;         for (unsigned j = 0; j < 16; ++j) { const unsigned c = xb_ld(&bar[XB_XCNT(j)]); sum += c; cnt += (c > 0u) ? 1u : 0u; mine = (j == x) ? c : mine; }
;         if (sum == G) break;
;         __builtin_amdgcn_s_sleep(1);
;         if ((++sp & 255u) == 0u) { if (xb_ld(&bar[XB_TMO])) break; if (sp > XB_SPIN_CAP) { atomicAdd(&bar[XB_TMO], 1u); break; } }
;     }
;     nloc = mine > 0u ? mine : 1u; nx = cnt > 0u ? cnt : 1u;
; }
; __device__ __forceinline__ void xcd_barrier(const XcdBarrier& b) {
;     asm volatile("s_waitcnt vmcnt(0)" ::: "memory");
;     __syncthreads();
;     if (threadIdx.x == 0) {
;         unsigned* bar = b.bar;
;         __builtin_amdgcn_s_waitcnt(0);
;         unsigned nloc = b.st[0], nx = b.st[1];
;         if (nloc == 0u) { xcd_barrier_complete(bar, b.x, nloc, nx); b.st[0] = nloc; b.st[1] = nx; }
;         const unsigned old = xb_add(&bar[XB_XSUB(b.x)], 1u);
;         const unsigned gen = old / nloc;
;         if (old + 1u == (gen + 1u) * nloc) {
.LBB0_851:
.LBB0_883:
	s_getreg_b32 s2, hwreg(HW_REG_XCC_ID, 0, 4)
	s_waitcnt vmcnt(0)
	s_barrier
	s_mov_b64 s[0:1], exec
	v_readlane_b32 s4, v254, 2
	v_readlane_b32 s5, v254, 3
	s_and_b64 s[4:5], s[0:1], s[4:5]
	s_mov_b64 exec, s[4:5]
	s_cbranch_execz .LBB0_927
	s_add_i32 s3, 0, 0x200c0
	v_mov_b32_e32 v0, s3
	s_waitcnt vmcnt(0) expcnt(0) lgkmcnt(0)
	ds_read_b32 v2, v0
	s_add_i32 s3, 0, 0x200c4
	v_mov_b32_e32 v0, s3
	ds_read_b32 v0, v0
	s_and_b32 s33, s2, 15
	s_waitcnt lgkmcnt(1)
	v_cmp_ne_u32_e32 vcc, 0, v2
	s_cbranch_vccnz .LBB0_898
	v_readlane_b32 s2, v254, 0
	v_readlane_b32 s3, v254, 1
	s_load_dwordx2 s[4:5], s[2:3], 0x4
	s_add_u32 s2, s80, 0xa0a200
	s_addc_u32 s3, s81, 0
	s_add_u32 s6, s80, 0xa0a400
	s_addc_u32 s7, s81, 0
	s_add_u32 s8, s80, 0xa0a500
	s_addc_u32 s9, s81, 0
	s_add_u32 s10, s80, 0xa0a600
	s_addc_u32 s11, s81, 0
	s_add_u32 s12, s80, 0xa0a700
	s_addc_u32 s13, s81, 0
	s_add_u32 s14, s80, 0xa0a800
	s_addc_u32 s15, s81, 0
	s_add_u32 s16, s80, 0xa0a900
	s_addc_u32 s17, s81, 0
	s_add_u32 s18, s80, 0xa0aa00
	s_addc_u32 s19, s81, 0
	s_add_u32 s20, s80, 0xa0ab00
	s_addc_u32 s21, s81, 0
	s_add_u32 s24, s80, 0xa0ac00
	s_addc_u32 s25, s81, 0
	s_add_u32 s26, s80, 0xa0ad00
	s_addc_u32 s27, s81, 0
	s_add_u32 s28, s80, 0xa0ae00
	s_addc_u32 s29, s81, 0
	s_add_u32 s30, s80, 0xa0af00
	s_addc_u32 s31, s81, 0
	s_add_u32 s34, s80, 0xa0b000
	s_addc_u32 s35, s81, 0
	s_add_u32 s36, s80, 0xa0b100
	s_addc_u32 s37, s81, 0
	s_add_u32 s38, s80, 0xa0b200
	s_addc_u32 s39, s81, 0
	s_add_u32 s40, s80, 0xa0b300
	s_waitcnt lgkmcnt(0)
	s_mul_i32 s22, s4, s84
	s_addc_u32 s41, s81, 0
	s_mul_i32 s22, s22, s5
	s_mov_b32 s23, 1
	s_mov_b64 s[4:5], 0
	v_mov_b64_e32 v[0:1], s[6:7]
	v_mov_b64_e32 v[2:3], s[8:9]
	v_mov_b64_e32 v[4:5], s[10:11]
	v_mov_b64_e32 v[6:7], s[12:13]
	v_mov_b64_e32 v[8:9], s[14:15]
	v_mov_b64_e32 v[10:11], s[16:17]
	v_mov_b64_e32 v[12:13], s[18:19]
	v_mov_b64_e32 v[14:15], s[20:21]
	v_mov_b64_e32 v[16:17], s[24:25]
	v_mov_b64_e32 v[18:19], s[26:27]
	v_mov_b64_e32 v[20:21], s[28:29]
	v_mov_b64_e32 v[22:23], s[30:31]
	v_mov_b64_e32 v[24:25], s[34:35]
	v_mov_b64_e32 v[26:27], s[36:37]
	v_mov_b64_e32 v[28:29], s[38:39]
	v_mov_b64_e32 v[30:31], s[40:41]
	s_branch .LBB0_888

; #define PG8_BAR __builtin_amdgcn_s_barrier()
; template <class Epi, class Sched, bool ALIGN_EPI = false, bool SP2 = false>
; __device__ __forceinline__ void gemm_phase(PG8_LAS unsigned char* lds, const Gemm g, const Sched& S, const Epi& E) {
;     ...
;     const int tid = tid_, wid = __builtin_amdgcn_readfirstlane(tid >> 6), lane = tid & 63, wr = wid >> 2, wc = wid & 3, fr = lane & 15, fq = lane >> 4;
;     const int K = g.K, nt = K / BK;
;     unsigned voffA, voffB;
;     { int R, C; stage_rc(tid * 16, R, C); const int Rb = Epi::PERM ? ((R & ~31) + perm32(R & 31)) : R;
;       voffA = (unsigned)(R * K + C) * 2u; voffB = (unsigned)(Rb * K + C) * 2u; }
;     const size_t rstep64 = (size_t)64 * K * 2;
;     const size_t kstep = (size_t)(BK * 2);
;     const size_t hstep = (size_t)HALF * K * 2;
;     const size_t tstep = 2 * hstep;
;     const unsigned ldsw = (unsigned)wid * 1024u;
;     const int aoff = lds_byte(wr * 64 + fr, fq * 8), boff = lds_byte(wc * 32 + fr, fq * 8);
;     ...
;     Unit cur, nxt; int ui = 0;
;     if (!S.next(0, cur)) return;
;     f32x4 acc[2][2][4][2];
; #pragma unroll
;     for (int a = 0; a < 2; ++a)
; #pragma unroll
;         for (int b = 0; b < 2; ++b)
; #pragma unroll
;             for (int m = 0; m < 4; ++m)
; #pragma unroll
;                 for (int n = 0; n < 2; ++n) acc[a][b][m][n] = (f32x4){0.f, 0.f, 0.f, 0.f};
;     bf16x8 At[4][2], B0[2][2], B1[2][2];
;     const char* cA = (const char*)g.A + (size_t)cur.pm * tstep; const char* cB = (const char*)g.Bt + (size_t)cur.pn * tstep;
;     S.a_ready(cur);
;     if constexpr (SP2) {
;         PG8_STAGE(PG8_SB(0, 0), cB, voffB); PG8_STAGE(PG8_SB(0, 1), cB + hstep, voffB); PG8_STAGE(PG8_SA(0, 0), cA, voffA); PG8_STAGE(PG8_SA(0, 1), cA + hstep, voffA);
;         if (wr == 1) PG8_BAR;
;         PG8_WAIT_V(2); PG8_BAR;
;         PG8_STAGE(PG8_SB(1, 0), cB + kstep, voffB); PG8_STAGE(PG8_SA(1, 0), cA + kstep, voffA); PG8_STAGE(PG8_SB(1, 1), cB + hstep + kstep, voffB);
;         PG8_WAIT_V(6); PG8_BAR;
;     } else {
; __global__ void __launch_bounds__(512, 2) mk_fwd(Args a) {
;     ...
;     { pg8::Gemm g{(const bt*)(ws + WS_MEMB), (const bt*)(ws + WS_WK), MEMR, DM, DM}; pg8::RangeOrder S; S.init(MEMR / 256, DM / 256, G, vb, 128);
;       pg8::EpiScale<1> E{(bt*)(ws + WS_KX), DM, (const float*)(ws + WS_RSTDMEM)};
;       pg8::gemm_phase<pg8::EpiScale<1>, pg8::RangeOrder, true, true>(lds, g, S, E); }
.LBB0_927:
	s_or_b64 exec, exec, s[0:1]
	s_waitcnt lgkmcnt(0)
	s_barrier
	s_add_u32 s33, s80, 0x1e000000
	s_addc_u32 s50, s81, 0
	s_abs_i32 s48, s84
	v_cvt_f32_u32_e32 v0, s48
	s_sub_i32 s0, 0, s48
	s_add_i32 s49, s84, s89
	v_mov_b32_e32 v4, v252
	v_rcp_iflag_f32_e32 v0, v0
	s_nop 0
	v_readfirstlane_b32 s20, v4
	v_mul_f32_e32 v0, 0x4f7ffffe, v0
	v_cvt_u32_f32_e32 v0, v0
	s_nop 0
	v_readfirstlane_b32 s51, v0
	s_mul_i32 s0, s0, s51
	s_mul_hi_u32 s0, s51, s0
	s_add_i32 s51, s51, s0
	s_lshr_b32 s0, s51, 25
	s_mul_i32 s0, s0, s48
	s_sub_i32 s0, 0x80, s0
	s_sub_i32 s1, s0, s48
	s_cmp_ge_u32 s0, s48
	s_cselect_b32 s0, s1, s0
	s_sub_i32 s1, s0, s48
	s_cmp_ge_u32 s0, s48
	s_cselect_b32 s0, s1, s0
	s_sub_i32 s0, s49, s0
	s_ashr_i32 s1, s0, 31
	s_abs_i32 s0, s0
	s_mul_hi_u32 s2, s0, s51
	s_mul_i32 s2, s2, s48
	s_sub_i32 s0, s0, s2
	s_sub_i32 s2, s0, s48
	s_cmp_ge_u32 s0, s48
	s_cselect_b32 s0, s2, s0
	s_sub_i32 s2, s0, s48
	s_cmp_ge_u32 s0, s48
	s_cselect_b32 s0, s2, s0
	s_xor_b32 s0, s0, s1
	s_sub_i32 s52, s0, s1
	s_add_u32 s0, s80, 0xa00000
	s_addc_u32 s1, s81, 0
	s_cmp_gt_i32 s52, 63
	s_cbranch_scc1 .LBB0_867
	v_bfe_i32 v1, v4, 27, 1
	v_lshlrev_b32_e32 v0, 4, v4
	v_lshrrev_b32_e32 v1, 22, v1
	v_add_u32_e32 v1, v0, v1
	v_and_b32_e32 v1, 0xfffffc00, v1
	v_sub_u32_e32 v0, v0, v1
	v_lshrrev_b32_e32 v1, 4, v0
	v_ashrrev_i32_e32 v2, 31, v4
	v_bitop3_b32 v0, v1, v0, 32 bitop3:0x6c
	v_lshrrev_b32_e32 v2, 26, v2
	v_ashrrev_i32_e32 v1, 31, v0
	v_add_u32_e32 v2, v4, v2
	v_lshrrev_b32_e32 v1, 26, v1
	v_ashrrev_i32_e32 v6, 6, v2
	v_add_u32_e32 v1, v0, v1
	v_lshlrev_b32_e32 v2, 3, v6
	s_add_u32 s53, s80, 0x3e00000
	v_ashrrev_i32_e32 v5, 6, v1
	v_and_b32_e32 v2, -16, v2
	s_addc_u32 s54, s81, 0
	v_add_u32_e32 v2, v5, v2
	v_and_b32_e32 v3, 3, v5
	s_mov_b32 s2, 0x1fffe0
	s_ashr_i32 s56, s52, 31
	v_and_or_b32 v3, v2, s2, v3
	s_lshr_b32 s2, s56, 30
	s_add_i32 s2, s52, s2
	v_lshrrev_b32_e32 v7, 2, v2
	v_lshlrev_b32_e32 v8, 1, v2
	v_and_b32_e32 v1, 0xc0, v1
	s_ashr_i32 s42, s2, 2
	s_and_b32 s2, s2, -4
	v_and_b32_e32 v7, 4, v7
	v_and_b32_e32 v8, 24, v8
	v_sub_u32_e32 v0, v0, v1
	v_mov_b32_e32 v1, 1
	s_sub_i32 s40, s52, s2
	s_ashr_i32 s21, s20, 6
	v_or3_b32 v3, v3, v7, v8
	v_lshlrev_b32_e32 v7, 5, v6
	v_ashrrev_i16_sdwa v0, v1, sext(v0) dst_sel:DWORD dst_unused:UNUSED_PAD src0_sel:DWORD src1_sel:BYTE_0
	s_ashr_i32 s43, s42, 31
	s_ashr_i32 s41, s40, 31
	s_ashr_i32 s22, s20, 8
	s_lshl_b32 s55, s21, 10
	v_and_b32_e32 v8, 32, v7
	v_bfe_i32 v7, v0, 0, 16
	s_lshl_b64 s[8:9], s[42:43], 19
	s_lshl_b64 s[2:3], s[40:41], 19
	v_add_lshl_u32 v0, v8, v7, 1
	s_add_u32 s46, s53, s2
	v_lshl_add_u32 v128, v3, 11, v0
	s_addc_u32 s47, s54, s3
	v_mov_b32_e32 v129, 0
	s_add_i32 s41, s55, 0
	v_lshl_add_u32 v130, v2, 11, v0
	v_lshl_add_u64 v[0:1], s[46:47], 0, v[128:129]
	s_add_i32 m0, s41, 0x10000
	s_mov_b64 s[2:3], 0x20000
	global_load_lds_dwordx4 v128, s[46:47]
	v_lshl_add_u64 v[2:3], v[0:1], 0, s[2:3]
	s_add_i32 m0, s41, 0x12000
	s_mov_b64 s[4:5], 0x40000
	global_load_lds_dwordx4 v[2:3], off
	v_lshl_add_u64 v[2:3], v[0:1], 0, s[4:5]
	s_add_i32 m0, s41, 0x14000
	s_mov_b64 s[6:7], 0x60000
	global_load_lds_dwordx4 v[2:3], off
	s_add_i32 m0, s41, 0x16000
	s_add_u32 s44, s33, s8
	v_lshl_add_u64 v[2:3], v[0:1], 0, s[6:7]
	s_addc_u32 s45, s50, s9
	v_mov_b32_e32 v131, v129
	global_load_lds_dwordx4 v[2:3], off
	v_lshl_add_u64 v[2:3], s[44:45], 0, v[130:131]
	s_mov_b32 m0, s41
	s_add_i32 s43, s41, 0x2000
	global_load_lds_dwordx4 v130, s[44:45]
	v_lshl_add_u64 v[8:9], v[2:3], 0, s[2:3]
	s_mov_b32 m0, s43
	s_add_i32 s57, s41, 0x4000
	global_load_lds_dwordx4 v[8:9], off
	v_lshl_add_u64 v[8:9], v[2:3], 0, s[4:5]
	s_mov_b32 m0, s57
	s_add_i32 s58, s41, 0x6000
	global_load_lds_dwordx4 v[8:9], off
	v_lshl_add_u64 v[8:9], v[2:3], 0, s[6:7]
	s_mov_b32 m0, s58
	s_cmp_eq_u32 s22, 1
	global_load_lds_dwordx4 v[8:9], off
	s_cselect_b64 s[8:9], -1, 0
	s_cmp_lg_u32 s22, 1
	s_cbranch_scc1 .LBB0_854
	s_barrier

; #define LAS __attribute__((address_space(3)))
; #define GAS __attribute__((address_space(1)))
; __device__ __forceinline__ unsigned xb_xcc_id() { return (unsigned)__builtin_amdgcn_s_getreg((3 << 11) | 20) & 0xFu; }
; #define FRESH_WS() asm volatile("" : "+s"(ws))
; __device__ __forceinline__ void prep_unit(const Args& a, LAS unsigned char* lds, int b, int kt, int tid) {
;     const GAS bf16* z = (const GAS bf16*)(a.ws + WS_Z);
;     LAS bf16* tT = (LAS bf16*)lds;
;     const int key = tid >> 3, ch = tid & 7; const size_t row = (size_t)b * SEQ + kt * 64 + key;
;     const u32x4 d0 = *(const GAS u32x4*)(z + row * ZW + ZDC + 16 * ch), d1 = *(const GAS u32x4*)(z + row * ZW + ZDC + 16 * ch + 8);
;     const u32x4 k0 = *(const GAS u32x4*)(z + row * ZW + ZIK + 8 * ch);
; __global__ void __launch_bounds__(512, 2) mk_fwd(Args a) {
;     ...
;     { XcdBarrier xbr; xbr.bar = (unsigned*)(ws + WS_XBAR); xbr.x = xb_xcc_id(); xbr.st = (volatile LAS unsigned*)(lds + 131072 + 192); xcd_barrier(xbr); } FRESH_WS();
;     { Args a4{}; a4.ws = ws; for (int u = vb; u < NB * 32 * DUP_PREP; u += G) prep_unit(a4, lds, (u >> 5) & 15, u & 31, tid); }
.Lp4_go:
	v_readlane_b32 s0, v254, 7
	v_readlane_b32 s1, v254, 8
	s_and_b64 vcc, exec, s[0:1]
	s_cbranch_vccnz .LBB0_930
	s_cmp_gt_u32 s89, 0x7f
	s_cbranch_scc1 .LBB0_930
	v_mbcnt_hi_u32_b32 v2, -1, v225
	v_and_b32_e32 v4, 64, v2
	v_xor_b32_e32 v3, 1, v2
	v_add_u32_e32 v4, 64, v4
	v_cmp_lt_i32_e32 vcc, v3, v4
	v_mov_b32_e32 v1, 0
	v_lshlrev_b32_e32 v8, 4, v252
	v_cndmask_b32_e32 v3, v2, v3, vcc
	v_lshlrev_b32_e32 v18, 2, v3
	v_xor_b32_e32 v3, 2, v2
	v_cmp_lt_i32_e32 vcc, v3, v4
	v_lshrrev_b32_e32 v6, 2, v252
	v_and_b32_e32 v16, 48, v8
	v_cndmask_b32_e32 v3, v2, v3, vcc
	v_lshlrev_b32_e32 v19, 2, v3
	v_xor_b32_e32 v3, 4, v2
	v_cmp_lt_i32_e32 vcc, v3, v4
	v_lshlrev_b32_e32 v0, 4, v226
	s_mov_b64 s[4:5], 0x1b400000
	v_cndmask_b32_e32 v2, v2, v3, vcc
	v_lshlrev_b32_e32 v20, 2, v2
	v_lshlrev_b32_e32 v2, 5, v226
	v_mov_b32_e32 v3, v1
	v_lshl_add_u64 v[2:3], s[80:81], 0, v[2:3]
	v_mul_u32_u24_e32 v7, 0x90, v6
	v_lshlrev_b32_e32 v8, 1, v16
	v_lshl_add_u64 v[2:3], v[2:3], 0, s[4:5]
	v_lshl_add_u64 v[4:5], s[80:81], 0, v[0:1]
	s_mov_b64 s[4:5], 0x1c400000
	v_add3_u32 v21, 0, v7, v8
	v_lshlrev_b32_e32 v6, 12, v6
	v_mov_b32_e32 v7, v1
	s_add_u32 s2, s80, 0x8400000
	v_lshrrev_b32_e32 v15, 3, v252
	v_lshl_add_u64 v[4:5], v[4:5], 0, s[4:5]
	v_lshl_add_u64 v[6:7], s[80:81], 0, v[6:7]
	s_mov_b64 s[4:5], 0x1bc00000
	s_addc_u32 s3, s81, 0
	v_lshlrev_b32_e32 v12, 3, v226
	v_lshl_add_u32 v17, v15, 1, 0
	v_mul_u32_u24_e32 v22, 0x900, v226
	v_lshl_add_u64 v[6:7], v[6:7], 0, s[4:5]
	s_mov_b32 s4, 0x3c800000
	s_mov_b32 s1, 0
	s_lshl_b32 s8, s89, 6
	s_movk_i32 s9, 0x2000
	s_movk_i32 s10, 0x1e00
	v_mov_b64_e32 v[8:9], s[2:3]
	v_lshlrev_b32_e32 v10, 1, v0
	v_mov_b32_e32 v11, v1
	s_mov_b64 s[2:3], 0x1800
	s_movk_i32 s11, 0x1000
	v_lshlrev_b32_e32 v12, 1, v12
	v_mov_b32_e32 v13, v1
	s_brev_b32 s5, 60
	v_mov_b32_e32 v14, 0x358637bd
	s_mov_b32 s12, 0x800000
	v_add_u32_e32 v22, v17, v22
	v_lshlrev_b32_e32 v16, 1, v16
	v_mov_b32_e32 v17, v1
	s_mov_b32 s13, s89
; __device__ __forceinline__ void prep_unit(const Args& a, LAS unsigned char* lds, int b, int kt, int tid) {
;     const GAS bf16* z = (const GAS bf16*)(a.ws + WS_Z);
;     LAS bf16* tT = (LAS bf16*)lds;
;     const int key = tid >> 3, ch = tid & 7; const size_t row = (size_t)b * SEQ + kt * 64 + key;
;     const u32x4 d0 = *(const GAS u32x4*)(z + row * ZW + ZDC + 16 * ch), d1 = *(const GAS u32x4*)(z + row * ZW + ZDC + 16 * ch + 8);
;     const u32x4 k0 = *(const GAS u32x4*)(z + row * ZW + ZIK + 8 * ch);
;     float v[16]; float ss = 0.f;
; #pragma unroll
;     for (int i = 0; i < 4; ++i) { v[2 * i] = bflo(d0[i]); v[2 * i + 1] = bfhi(d0[i]); v[8 + 2 * i] = bflo(d1[i]); v[8 + 2 * i + 1] = bfhi(d1[i]); }
; #pragma unroll
;     for (int i = 0; i < 16; ++i) ss += v[i] * v[i];
;     ss += __shfl_xor(ss, 1); ss += __shfl_xor(ss, 2); ss += __shfl_xor(ss, 4);
;     const float r = rsqrtf(ss * (1.f / 128.f) + EPS);
;     unsigned short o[16];
;     u32x4 w0, w1;
; #pragma unroll
;     for (int i = 0; i < 4; ++i) { w0[i] = pk2(v[2 * i] * r, v[2 * i + 1] * r); w1[i] = pk2(v[8 + 2 * i] * r, v[8 + 2 * i + 1] * r);
;         o[2 * i] = (unsigned short)(w0[i] & 0xffffu); o[2 * i + 1] = (unsigned short)(w0[i] >> 16); o[8 + 2 * i] = (unsigned short)(w1[i] & 0xffffu); o[8 + 2 * i + 1] = (unsigned short)(w1[i] >> 16); }
;     GAS bf16* ckv = (GAS bf16*)(a.ws + WS_CKV);
;     *(GAS u32x4*)(ckv + row * 128 + 16 * ch) = w0; *(GAS u32x4*)(ckv + row * 128 + 16 * ch + 8) = w1;
; #pragma unroll
;     for (int i = 0; i < 16; ++i) tT[(16 * ch + i) * 72 + key] = o[i];
;     float kv[8]; float s2 = 0.f;
; #pragma unroll
;     for (int i = 0; i < 4; ++i) { kv[2 * i] = bflo(k0[i]); kv[2 * i + 1] = bfhi(k0[i]); }
; #pragma unroll
;     for (int i = 0; i < 8; ++i) s2 += kv[i] * kv[i];
;     s2 += __shfl_xor(s2, 1); s2 += __shfl_xor(s2, 2); s2 += __shfl_xor(s2, 4);
;     const float r2 = rsqrtf(s2 * (1.f / 64.f) + EPS);
;     u32x4 wk;
; #pragma unroll
;     for (int i = 0; i < 4; ++i) wk[i] = pk2(kv[2 * i] * r2, kv[2 * i + 1] * r2);
;     *(GAS u32x4*)((GAS bf16*)(a.ws + WS_IKN) + row * 64 + 8 * ch) = wk;
;     __syncthreads();
;     const int c = tid >> 2, q4 = tid & 3;
;     const u32x4 t0 = *(const LAS u32x4*)(tT + c * 72 + 16 * q4), t1 = *(const LAS u32x4*)(tT + c * 72 + 16 * q4 + 8);
;     GAS bf16* dst = (GAS bf16*)(a.ws + WS_CKVT) + ((size_t)b * 128 + c) * SEQ + kt * 64 + 16 * q4;
.LBB0_929:
	s_bfe_u32 s0, s13, 0x40005
	s_and_b32 s6, s8, 0x7c0
	s_lshl_b32 s7, s0, 11
	s_lshl_b32 s0, s0, 19
	s_or_b32 s7, s7, s6
	v_lshl_add_u64 v[24:25], v[6:7], 0, s[0:1]
	s_lshl_b32 s0, s6, 1
	v_add_u32_e32 v23, s7, v15
	v_lshl_add_u64 v[24:25], v[24:25], 0, s[0:1]
	v_mad_u64_u32 v[26:27], s[6:7], v23, s10, v[8:9]
	v_lshl_add_u64 v[36:37], v[24:25], 0, v[16:17]
	v_lshl_add_u64 v[24:25], v[26:27], 0, v[10:11]
	v_add_co_u32_e32 v40, vcc, 0x1000, v24
	v_lshl_add_u64 v[32:33], v[26:27], 0, v[12:13]
	v_lshl_add_u64 v[34:35], v[24:25], 0, s[2:3]
	v_addc_co_u32_e32 v41, vcc, 0, v25, vcc
	v_add_co_u32_e32 v32, vcc, s11, v32
	global_load_dwordx4 v[24:27], v[34:35], off offset:16
	global_load_dwordx4 v[28:31], v[40:41], off offset:2048
	v_addc_co_u32_e32 v33, vcc, 0, v33, vcc
	global_load_dwordx4 v[32:35], v[32:33], off offset:3328
	v_lshlrev_b32_e32 v0, 8, v23
	v_lshl_add_u64 v[38:39], v[2:3], 0, v[0:1]
	v_lshlrev_b32_e32 v0, 7, v23
	v_lshl_add_u64 v[42:43], v[4:5], 0, v[0:1]
	s_addk_i32 s13, 0x80
	s_add_i32 s8, s8, s9
	s_cmpk_gt_i32 s13, 0x1ff
	s_waitcnt vmcnt(0)
	v_lshlrev_b32_e32 v40, 16, v27
	v_and_b32_e32 v53, 0xffff0000, v28
	v_lshlrev_b32_e32 v52, 16, v28
	v_mul_f32_e32 v0, v53, v53
	v_lshlrev_b32_e32 v48, 16, v29
	v_and_b32_e32 v49, 0xffff0000, v29
	v_lshlrev_b32_e32 v64, 16, v35
	v_and_b32_e32 v65, 0xffff0000, v35
	v_lshlrev_b32_e32 v66, 16, v34
	v_and_b32_e32 v67, 0xffff0000, v34
	v_lshlrev_b32_e32 v34, 16, v33
	v_and_b32_e32 v35, 0xffff0000, v33
	v_lshlrev_b32_e32 v68, 16, v32
	v_and_b32_e32 v69, 0xffff0000, v32
	v_pk_fma_f32 v[32:33], v[52:53], v[52:53], v[0:1] op_sel_hi:[1,1,0]
	v_mul_f32_e32 v58, v49, v49
	v_pk_fma_f32 v[32:33], v[48:49], v[48:49], v[32:33]
	v_and_b32_e32 v41, 0xffff0000, v27
	v_lshlrev_b32_e32 v46, 16, v26
	v_and_b32_e32 v47, 0xffff0000, v26
	v_lshlrev_b32_e32 v26, 16, v30
	v_and_b32_e32 v27, 0xffff0000, v30
	v_pk_add_f32 v[32:33], v[58:59], v[32:33] op_sel_hi:[0,1]
	v_mul_f32_e32 v60, v27, v27
	v_pk_fma_f32 v[32:33], v[26:27], v[26:27], v[32:33]
	v_lshlrev_b32_e32 v44, 16, v31
	v_and_b32_e32 v45, 0xffff0000, v31
	v_pk_add_f32 v[32:33], v[60:61], v[32:33] op_sel_hi:[0,1]
	v_lshlrev_b32_e32 v30, 16, v25
	v_and_b32_e32 v31, 0xffff0000, v25
	v_and_b32_e32 v25, 0xffff0000, v24
	v_mul_f32_e32 v62, v45, v45
	v_pk_fma_f32 v[32:33], v[44:45], v[44:45], v[32:33]
	v_lshlrev_b32_e32 v50, 16, v24
	v_and_b32_e32 v24, s0, v24
	v_mov_b32_e32 v51, v25
	v_pk_add_f32 v[32:33], v[62:63], v[32:33] op_sel_hi:[0,1]
	v_pk_mul_f32 v[24:25], v[24:25], v[24:25]
	v_pk_mul_f32 v[76:77], v[68:69], v[68:69]
	v_pk_fma_f32 v[32:33], v[50:51], v[50:51], v[32:33]
	v_pk_mul_f32 v[56:57], v[30:31], v[30:31]
	v_pk_mul_f32 v[74:75], v[34:35], v[34:35]
	v_mov_b32_e32 v24, v76
	v_pk_mov_b32 v[32:33], v[76:77], v[32:33] op_sel:[1,0]
	v_mov_b32_e32 v79, v56
	v_mov_b32_e32 v78, v74
	v_pk_add_f32 v[24:25], v[24:25], v[32:33]
	v_pk_mul_f32 v[54:55], v[46:47], v[46:47]
	v_pk_mul_f32 v[72:73], v[66:67], v[66:67]
	v_mov_b32_e32 v56, v75
	v_pk_add_f32 v[24:25], v[78:79], v[24:25]
	v_mov_b32_e32 v81, v54
	v_mov_b32_e32 v80, v72
	v_pk_add_f32 v[24:25], v[56:57], v[24:25]
	v_pk_mul_f32 v[28:29], v[40:41], v[40:41]
	v_pk_mul_f32 v[70:71], v[64:65], v[64:65]
	v_mov_b32_e32 v54, v73
	v_pk_add_f32 v[24:25], v[80:81], v[24:25]
	v_mov_b32_e32 v83, v28
	v_mov_b32_e32 v82, v70
	v_pk_add_f32 v[24:25], v[54:55], v[24:25]
	v_mov_b32_e32 v28, v71
	v_pk_add_f32 v[24:25], v[82:83], v[24:25]
	s_nop 0
	v_pk_add_f32 v[24:25], v[28:29], v[24:25]
	ds_bpermute_b32 v29, v18, v25
	ds_bpermute_b32 v28, v18, v24
	s_waitcnt lgkmcnt(0)
	v_pk_add_f32 v[24:25], v[24:25], v[28:29]
	ds_bpermute_b32 v29, v19, v25
	ds_bpermute_b32 v28, v19, v24
	s_waitcnt lgkmcnt(0)
	v_pk_add_f32 v[24:25], v[24:25], v[28:29]
	ds_bpermute_b32 v29, v20, v25
	ds_bpermute_b32 v28, v20, v24
	s_waitcnt lgkmcnt(0)
	v_pk_add_f32 v[24:25], v[24:25], v[28:29]
	s_nop 0
	v_pk_fma_f32 v[24:25], v[24:25], s[4:5], v[14:15] op_sel_hi:[1,1,0]
	s_nop 0
	v_mul_f32_e32 v0, 0x4b800000, v25
	v_mul_f32_e32 v23, 0x4b800000, v24
	v_cmp_gt_f32_e32 vcc, s12, v24
	v_cmp_gt_f32_e64 s[6:7], s12, v25
	s_nop 0
	v_cndmask_b32_e32 v23, v24, v23, vcc
	v_cndmask_b32_e64 v0, v25, v0, s[6:7]
	v_rsq_f32_e32 v0, v0
	v_rsq_f32_e32 v23, v23
	v_mul_f32_e32 v24, 0x45800000, v0
	v_mul_f32_e32 v25, 0x45800000, v23
	v_cndmask_b32_e64 v0, v0, v24, s[6:7]
	v_cndmask_b32_e32 v24, v23, v25, vcc
	v_pk_mul_f32 v[28:29], v[0:1], v[52:53] op_sel_hi:[0,1]
	v_pk_mul_f32 v[32:33], v[0:1], v[50:51] op_sel_hi:[0,1]
	v_pk_mul_f32 v[48:49], v[0:1], v[48:49] op_sel_hi:[0,1]
	v_pk_mul_f32 v[30:31], v[0:1], v[30:31] op_sel_hi:[0,1]
	v_pk_mul_f32 v[26:27], v[0:1], v[26:27] op_sel_hi:[0,1]
	v_pk_mul_f32 v[46:47], v[0:1], v[46:47] op_sel_hi:[0,1]
	v_pk_mul_f32 v[44:45], v[0:1], v[44:45] op_sel_hi:[0,1]
	v_pk_mul_f32 v[40:41], v[0:1], v[40:41] op_sel_hi:[0,1]
	v_pk_mul_f32 v[50:51], v[24:25], v[68:69] op_sel_hi:[0,1]
	v_pk_mul_f32 v[34:35], v[24:25], v[34:35] op_sel_hi:[0,1]
	v_pk_mul_f32 v[52:53], v[24:25], v[66:67] op_sel_hi:[0,1]
	v_pk_mul_f32 v[54:55], v[24:25], v[64:65] op_sel_hi:[0,1]
	v_cvt_pk_bf16_f32 v24, v28, v29
	v_cvt_pk_bf16_f32 v28, v32, v33
	v_cvt_pk_bf16_f32 v25, v48, v49
	v_cvt_pk_bf16_f32 v29, v30, v31
	v_cvt_pk_bf16_f32 v26, v26, v27
	v_cvt_pk_bf16_f32 v30, v46, v47
	v_cvt_pk_bf16_f32 v27, v44, v45
	v_cvt_pk_bf16_f32 v31, v40, v41
	v_cvt_pk_bf16_f32 v32, v50, v51
	v_cvt_pk_bf16_f32 v33, v34, v35
	v_cvt_pk_bf16_f32 v34, v52, v53
	v_cvt_pk_bf16_f32 v35, v54, v55
	global_store_dwordx4 v[38:39], v[24:27], off
	global_store_dwordx4 v[38:39], v[28:31], off offset:16
	ds_write_b16 v22, v24
	ds_write_b16_d16_hi v22, v24 offset:144
	ds_write_b16 v22, v25 offset:288
	ds_write_b16_d16_hi v22, v25 offset:432
	ds_write_b16 v22, v26 offset:576
	ds_write_b16_d16_hi v22, v26 offset:720
	ds_write_b16 v22, v27 offset:864
	ds_write_b16_d16_hi v22, v27 offset:1008
	ds_write_b16 v22, v28 offset:1152
	ds_write_b16_d16_hi v22, v28 offset:1296
	ds_write_b16 v22, v29 offset:1440
	ds_write_b16_d16_hi v22, v29 offset:1584
	ds_write_b16 v22, v30 offset:1728
	ds_write_b16_d16_hi v22, v30 offset:1872
	ds_write_b16 v22, v31 offset:2016
	ds_write_b16_d16_hi v22, v31 offset:2160
	global_store_dwordx4 v[42:43], v[32:35], off
	s_waitcnt lgkmcnt(0)
	s_barrier
	ds_read_b128 v[24:27], v21
	ds_read_b128 v[28:31], v21 offset:16
	s_waitcnt lgkmcnt(1)
	global_store_dwordx4 v[36:37], v[24:27], off
	s_waitcnt lgkmcnt(0)
	global_store_dwordx4 v[36:37], v[28:31], off offset:16
	s_barrier
	s_cbranch_scc0 .LBB0_929
